# P5 tail: the short K part (attention branch) writes mix first and the long K part (SSM branch) does the read-modify-write, so the wait sits behind the long K loop
# speedup vs baseline: 1.0144x; 1.0034x over previous
;     __device__ __forceinline__ void operator()(const f32x4 (&acc)[2][2][4][2], const Unit& u, int wr, int wc, int fr, int fq) const {
;     ...
;         const int gbase = u.part == 0 ? C_GS : C_GA;
; #pragma unroll
;         for (int ai = 0; ai < 2; ++ai) {
; #pragma unroll
;             for (int mp = 0; mp < 2; ++mp) {
;             u32x4 gw[2][2], pw[2][2];
; #pragma unroll
;             for (int mm = 0; mm < 2; ++mm) { const int row = row0 + ai * HALF + (2 * mp + mm) * 16;
; #pragma unroll
;                 for (int bj = 0; bj < 2; ++bj) { const int col = col0 + bj * HALF;
;                     gw[mm][bj] = *(const u32x4*)(proj + (size_t)row * PN + gbase + col);
;                     pw[mm][bj] = u.part == 1 ? *(const u32x4*)(mix + (size_t)row * DM + col) : (u32x4){0u, 0u, 0u, 0u}; } }
.LBB0_684:
	s_cmp_eq_u32 s100, 1
	s_cselect_b64 s[14:15], -1, s[14:15]
	s_cmp_eq_u32 s100, 2
	s_cselect_b64 s[14:15], 0, s[14:15]
	s_cmp_eq_u32 s100, 1
	s_cbranch_scc0 .Lpp5_nw
	v_readfirstlane_b32 s20, v166
	s_nop 0
	s_cmp_lt_u32 s20, 64
	s_cbranch_scc0 .Lpp5_wb
	v_readlane_b32 s21, v252, 2
	s_lshr_b32 s21, s21, 9
	s_lshl_b32 s21, s21, 2
	s_addk_i32 s21, 0x3700
	v_mov_b32_e32 v188, s21
	s_add_u32 s4, s26, 0x1d780000
	s_addc_u32 s5, s27, 0
	s_mov_b32 s28, 0

; __device__ __forceinline__ unsigned pk2(float lo, float hi) { unsigned r; asm("v_cvt_pk_bf16_f32 %0, %1, %2" : "=v"(r) : "v"(lo), "v"(hi)); return r; }
; __device__ __forceinline__ float bflo(unsigned w) { return __uint_as_float(w << 16); }
; __device__ __forceinline__ float bfhi(unsigned w) { return __uint_as_float(w & 0xffff0000u); }
; __device__ __forceinline__ float sigmoidf_(float x) { return __builtin_amdgcn_rcpf(1.f + __expf(-x)); }
;     __device__ __forceinline__ void operator()(const f32x4 (&acc)[2][2][4][2], const Unit& u, int wr, int wc, int fr, int fq) const {
;     ...
;             for (int mm = 0; mm < 2; ++mm) { const int m = 2 * mp + mm; const int row = row0 + ai * HALF + m * 16;
; #pragma unroll
;                 for (int bj = 0; bj < 2; ++bj) { const int col = col0 + bj * HALF;
;                     const u32x4 g = gw[mm][bj], p = pw[mm][bj];
;                     const f32x4 v0 = acc[ai][bj][m][0], v1 = acc[ai][bj][m][1];
;                     float r[8];
;                     r[0] = sigmoidf_(bflo(g.x)) * v0[0] + bflo(p.x); r[1] = sigmoidf_(bfhi(g.x)) * v0[1] + bfhi(p.x); r[2] = sigmoidf_(bflo(g.y)) * v0[2] + bflo(p.y); r[3] = sigmoidf_(bfhi(g.y)) * v0[3] + bfhi(p.y);
;                     r[4] = sigmoidf_(bflo(g.z)) * v1[0] + bflo(p.z); r[5] = sigmoidf_(bfhi(g.z)) * v1[1] + bfhi(p.z); r[6] = sigmoidf_(bflo(g.w)) * v1[2] + bflo(p.w); r[7] = sigmoidf_(bfhi(g.w)) * v1[3] + bfhi(p.w);
;                     u32x4 w; w.x = pk2(r[0], r[1]); w.y = pk2(r[2], r[3]); w.z = pk2(r[4], r[5]); w.w = pk2(r[6], r[7]);
;                     *(u32x4*)(mix + (size_t)row * DM + col) = w; } }
.LBB0_716:
	s_waitcnt vmcnt(3)
	v_lshlrev_b32_e32 v0, 16, v60
	v_mul_f32_e32 v0, 0xbfb8aa3b, v0
	v_exp_f32_e32 v0, v0
	v_and_b32_e32 v3, 0xffff0000, v60
	v_mul_f32_e32 v3, 0xbfb8aa3b, v3
	v_lshlrev_b32_e32 v60, 16, v61
	v_add_f32_e32 v0, 1.0, v0
	v_rcp_f32_e32 v0, v0
	v_exp_f32_e32 v3, v3
	v_mul_f32_e32 v60, 0xbfb8aa3b, v60
	v_exp_f32_e32 v60, v60
	v_lshlrev_b32_e32 v2, 16, v68
	v_fmac_f32_e32 v2, v32, v0
	v_add_f32_e32 v0, 1.0, v3
	v_rcp_f32_e32 v0, v0
	v_add_f32_e32 v3, 1.0, v60
	v_rcp_f32_e32 v3, v3
	v_and_b32_e32 v32, 0xffff0000, v68
	v_fmac_f32_e32 v32, v33, v0
	v_lshlrev_b32_e32 v0, 16, v69
	v_fmac_f32_e32 v0, v34, v3
	v_and_b32_e32 v3, 0xffff0000, v61
	v_mul_f32_e32 v3, 0xbfb8aa3b, v3
	v_lshlrev_b32_e32 v33, 16, v62
	v_exp_f32_e32 v3, v3
	v_mul_f32_e32 v33, 0xbfb8aa3b, v33
	v_exp_f32_e32 v33, v33
	v_and_b32_e32 v60, 0xffff0000, v62
	v_add_f32_e32 v3, 1.0, v3
	v_rcp_f32_e32 v3, v3
	v_add_f32_e32 v33, 1.0, v33
	v_mul_f32_e32 v60, 0xbfb8aa3b, v60
	v_rcp_f32_e32 v33, v33
	v_exp_f32_e32 v60, v60
	v_and_b32_e32 v34, 0xffff0000, v69
	v_fmac_f32_e32 v34, v35, v3
	v_lshlrev_b32_e32 v3, 16, v70
	v_fmac_f32_e32 v3, v28, v33
	v_add_f32_e32 v28, 1.0, v60
	v_and_b32_e32 v60, 0xffff0000, v63
	v_mul_f32_e32 v60, 0xbfb8aa3b, v60
	v_rcp_f32_e32 v28, v28
	v_exp_f32_e32 v60, v60
	v_lshlrev_b32_e32 v35, 16, v63
	v_and_b32_e32 v33, 0xffff0000, v70
	v_mul_f32_e32 v35, 0xbfb8aa3b, v35
	v_exp_f32_e32 v35, v35
	v_fmac_f32_e32 v33, v29, v28
	v_add_f32_e32 v29, 1.0, v60
	v_rcp_f32_e32 v29, v29
	v_add_f32_e32 v28, 1.0, v35
	v_and_b32_e32 v60, 0xffff0000, v71
	v_rcp_f32_e32 v28, v28
	v_fmac_f32_e32 v60, v31, v29
	v_cvt_pk_bf16_f32 v29, v0, v34
	s_waitcnt vmcnt(2)
	v_lshlrev_b32_e32 v0, 16, v56
	v_mul_f32_e32 v0, 0xbfb8aa3b, v0
	v_exp_f32_e32 v0, v0
	v_lshlrev_b32_e32 v35, 16, v71
	v_fmac_f32_e32 v35, v30, v28
	v_cvt_pk_bf16_f32 v28, v2, v32
	v_cvt_pk_bf16_f32 v30, v3, v33
	v_lshl_add_u64 v[2:3], v[66:67], 0, v[158:159]
	v_cvt_pk_bf16_f32 v31, v35, v60
	global_store_dwordx4 v[2:3], v[28:31], off sc0 sc1
	v_add_f32_e32 v0, 1.0, v0
	v_rcp_f32_e32 v0, v0
	v_and_b32_e32 v29, 0xffff0000, v56
	v_mul_f32_e32 v29, 0xbfb8aa3b, v29
	v_lshlrev_b32_e32 v30, 16, v57
	v_exp_f32_e32 v29, v29
	v_mul_f32_e32 v30, 0xbfb8aa3b, v30
	v_exp_f32_e32 v30, v30
	v_lshlrev_b32_e32 v28, 16, v52
	v_fmac_f32_e32 v28, v24, v0
	v_add_f32_e32 v0, 1.0, v29
	v_rcp_f32_e32 v0, v0
	v_add_f32_e32 v24, 1.0, v30
	v_rcp_f32_e32 v24, v24
	v_and_b32_e32 v29, 0xffff0000, v52
	v_fmac_f32_e32 v29, v25, v0
	v_lshlrev_b32_e32 v0, 16, v53
	v_fmac_f32_e32 v0, v26, v24
	v_and_b32_e32 v24, 0xffff0000, v57
	v_mul_f32_e32 v24, 0xbfb8aa3b, v24
	v_lshlrev_b32_e32 v25, 16, v58
	v_exp_f32_e32 v24, v24
	v_mul_f32_e32 v25, 0xbfb8aa3b, v25
	v_exp_f32_e32 v25, v25
	v_and_b32_e32 v30, 0xffff0000, v58
	v_add_f32_e32 v24, 1.0, v24
	v_rcp_f32_e32 v24, v24
	v_add_f32_e32 v25, 1.0, v25
	v_mul_f32_e32 v30, 0xbfb8aa3b, v30
	v_rcp_f32_e32 v25, v25
	v_exp_f32_e32 v30, v30
	v_and_b32_e32 v26, 0xffff0000, v53
	v_fmac_f32_e32 v26, v27, v24
	v_lshlrev_b32_e32 v24, 16, v54
	v_fmac_f32_e32 v24, v20, v25
	v_add_f32_e32 v20, 1.0, v30
	v_and_b32_e32 v30, 0xffff0000, v59
	v_mul_f32_e32 v30, 0xbfb8aa3b, v30
	v_rcp_f32_e32 v20, v20
	v_exp_f32_e32 v30, v30
	v_and_b32_e32 v25, 0xffff0000, v54
	v_lshlrev_b32_e32 v27, 16, v59
	v_mul_f32_e32 v27, 0xbfb8aa3b, v27
	v_fmac_f32_e32 v25, v21, v20
	v_add_f32_e32 v21, 1.0, v30
	v_exp_f32_e32 v27, v27
	v_rcp_f32_e32 v21, v21
	v_and_b32_e32 v30, 0xffff0000, v55
	s_and_b64 vcc, exec, s[40:41]
	v_add_f32_e32 v20, 1.0, v27
	v_fmac_f32_e32 v30, v23, v21
	v_cvt_pk_bf16_f32 v21, v0, v26
	s_waitcnt vmcnt(2)
; __device__ __forceinline__ unsigned pk2(float lo, float hi) { unsigned r; asm("v_cvt_pk_bf16_f32 %0, %1, %2" : "=v"(r) : "v"(lo), "v"(hi)); return r; }
; __device__ __forceinline__ float bflo(unsigned w) { return __uint_as_float(w << 16); }
; __device__ __forceinline__ float bfhi(unsigned w) { return __uint_as_float(w & 0xffff0000u); }
; __device__ __forceinline__ float sigmoidf_(float x) { return __builtin_amdgcn_rcpf(1.f + __expf(-x)); }
;     __device__ __forceinline__ void operator()(const f32x4 (&acc)[2][2][4][2], const Unit& u, int wr, int wc, int fr, int fq) const {
;     ...
;             for (int mm = 0; mm < 2; ++mm) { const int m = 2 * mp + mm; const int row = row0 + ai * HALF + m * 16;
; #pragma unroll
;                 for (int bj = 0; bj < 2; ++bj) { const int col = col0 + bj * HALF;
;                     const u32x4 g = gw[mm][bj], p = pw[mm][bj];
;                     const f32x4 v0 = acc[ai][bj][m][0], v1 = acc[ai][bj][m][1];
;                     float r[8];
;                     r[0] = sigmoidf_(bflo(g.x)) * v0[0] + bflo(p.x); r[1] = sigmoidf_(bfhi(g.x)) * v0[1] + bfhi(p.x); r[2] = sigmoidf_(bflo(g.y)) * v0[2] + bflo(p.y); r[3] = sigmoidf_(bfhi(g.y)) * v0[3] + bfhi(p.y);
;                     r[4] = sigmoidf_(bflo(g.z)) * v1[0] + bflo(p.z); r[5] = sigmoidf_(bfhi(g.z)) * v1[1] + bfhi(p.z); r[6] = sigmoidf_(bflo(g.w)) * v1[2] + bflo(p.w); r[7] = sigmoidf_(bfhi(g.w)) * v1[3] + bfhi(p.w);
;                     u32x4 w; w.x = pk2(r[0], r[1]); w.y = pk2(r[2], r[3]); w.z = pk2(r[4], r[5]); w.w = pk2(r[6], r[7]);
;                     *(u32x4*)(mix + (size_t)row * DM + col) = w; } }
	v_lshlrev_b32_e32 v0, 16, v48
	v_rcp_f32_e32 v20, v20
	v_mul_f32_e32 v0, 0xbfb8aa3b, v0
	v_exp_f32_e32 v0, v0
	v_lshlrev_b32_e32 v27, 16, v55
	v_fmac_f32_e32 v27, v22, v20
	v_cvt_pk_bf16_f32 v20, v28, v29
	v_cvt_pk_bf16_f32 v22, v24, v25
	v_cvt_pk_bf16_f32 v23, v27, v30
	global_store_dwordx4 v[2:3], v[20:23], off offset:256 sc0 sc1
	v_and_b32_e32 v3, 0xffff0000, v48
	v_add_f32_e32 v0, 1.0, v0
	v_mul_f32_e32 v3, 0xbfb8aa3b, v3
	v_lshlrev_b32_e32 v20, 16, v49
	v_rcp_f32_e32 v0, v0
	v_exp_f32_e32 v3, v3
	v_mul_f32_e32 v20, 0xbfb8aa3b, v20
	v_exp_f32_e32 v20, v20
	v_lshlrev_b32_e32 v2, 16, v44
	v_fmac_f32_e32 v2, v16, v0
	v_add_f32_e32 v0, 1.0, v3
	v_rcp_f32_e32 v0, v0
	v_add_f32_e32 v3, 1.0, v20
	v_rcp_f32_e32 v3, v3
	v_and_b32_e32 v16, 0xffff0000, v44
	v_fmac_f32_e32 v16, v17, v0
	v_lshlrev_b32_e32 v0, 16, v45
	v_fmac_f32_e32 v0, v18, v3
	v_and_b32_e32 v3, 0xffff0000, v49
	v_mul_f32_e32 v3, 0xbfb8aa3b, v3
	v_lshlrev_b32_e32 v17, 16, v50
	v_exp_f32_e32 v3, v3
	v_mul_f32_e32 v17, 0xbfb8aa3b, v17
	v_exp_f32_e32 v17, v17
	v_and_b32_e32 v20, 0xffff0000, v50
	v_add_f32_e32 v3, 1.0, v3
	v_rcp_f32_e32 v3, v3
	v_add_f32_e32 v17, 1.0, v17
	v_mul_f32_e32 v20, 0xbfb8aa3b, v20
	v_rcp_f32_e32 v17, v17
	v_exp_f32_e32 v20, v20
	v_and_b32_e32 v18, 0xffff0000, v45
	v_fmac_f32_e32 v18, v19, v3
	v_lshlrev_b32_e32 v3, 16, v46
	v_fmac_f32_e32 v3, v12, v17
	v_add_f32_e32 v12, 1.0, v20
	v_and_b32_e32 v20, 0xffff0000, v51
	v_mul_f32_e32 v20, 0xbfb8aa3b, v20
	v_rcp_f32_e32 v12, v12
	v_exp_f32_e32 v20, v20
	v_and_b32_e32 v17, 0xffff0000, v46
	v_lshlrev_b32_e32 v19, 16, v51
	v_mul_f32_e32 v19, 0xbfb8aa3b, v19
	v_fmac_f32_e32 v17, v13, v12
	v_add_f32_e32 v13, 1.0, v20
	v_exp_f32_e32 v19, v19
	v_rcp_f32_e32 v13, v13
	v_and_b32_e32 v20, 0xffff0000, v47
	s_mov_b64 s[4:5], -1
	v_add_f32_e32 v12, 1.0, v19
	v_fmac_f32_e32 v20, v15, v13
	v_cvt_pk_bf16_f32 v13, v0, v18
	s_waitcnt vmcnt(2)
	v_lshlrev_b32_e32 v0, 16, v40
	v_rcp_f32_e32 v12, v12
	v_mul_f32_e32 v0, 0xbfb8aa3b, v0
	v_exp_f32_e32 v0, v0
	v_lshlrev_b32_e32 v19, 16, v47
	v_fmac_f32_e32 v19, v14, v12
	v_cvt_pk_bf16_f32 v12, v2, v16
	v_cvt_pk_bf16_f32 v14, v3, v17
	v_lshl_add_u64 v[16:17], v[64:65], 0, v[158:159]
	v_and_b32_e32 v3, 0xffff0000, v40
	v_cvt_pk_bf16_f32 v15, v19, v20
	global_store_dwordx4 v[16:17], v[12:15], off sc0 sc1
	v_add_f32_e32 v0, 1.0, v0
	v_mul_f32_e32 v3, 0xbfb8aa3b, v3
	v_lshlrev_b32_e32 v12, 16, v41
	v_rcp_f32_e32 v0, v0
	v_exp_f32_e32 v3, v3
	v_mul_f32_e32 v12, 0xbfb8aa3b, v12
	v_exp_f32_e32 v12, v12
	v_lshlrev_b32_e32 v2, 16, v36
	v_fmac_f32_e32 v2, v8, v0
	v_add_f32_e32 v0, 1.0, v3
	v_rcp_f32_e32 v0, v0
	v_add_f32_e32 v3, 1.0, v12
	v_rcp_f32_e32 v3, v3
	v_and_b32_e32 v8, 0xffff0000, v36
	v_fmac_f32_e32 v8, v9, v0
	v_lshlrev_b32_e32 v0, 16, v37
	v_fmac_f32_e32 v0, v10, v3
	v_and_b32_e32 v3, 0xffff0000, v41
	v_mul_f32_e32 v3, 0xbfb8aa3b, v3
	v_lshlrev_b32_e32 v9, 16, v42
	v_exp_f32_e32 v3, v3
	v_mul_f32_e32 v9, 0xbfb8aa3b, v9
	v_exp_f32_e32 v9, v9
	v_and_b32_e32 v12, 0xffff0000, v42
	v_add_f32_e32 v3, 1.0, v3
	v_rcp_f32_e32 v3, v3
	v_add_f32_e32 v9, 1.0, v9
	v_rcp_f32_e32 v9, v9
	v_mul_f32_e32 v12, 0xbfb8aa3b, v12
	v_exp_f32_e32 v12, v12
	v_and_b32_e32 v10, 0xffff0000, v37
	v_fmac_f32_e32 v10, v11, v3
	v_lshlrev_b32_e32 v11, 16, v38
	v_fmac_f32_e32 v11, v4, v9
	v_lshlrev_b32_e32 v9, 16, v43
	v_add_f32_e32 v3, 1.0, v12
	v_mul_f32_e32 v9, 0xbfb8aa3b, v9
	v_and_b32_e32 v12, 0xffff0000, v43
	v_rcp_f32_e32 v3, v3
	v_exp_f32_e32 v9, v9
	v_mul_f32_e32 v12, 0xbfb8aa3b, v12
	v_exp_f32_e32 v12, v12
	v_and_b32_e32 v4, 0xffff0000, v38
	v_fmac_f32_e32 v4, v5, v3
	v_add_f32_e32 v3, 1.0, v9
	v_rcp_f32_e32 v3, v3
	v_add_f32_e32 v5, 1.0, v12
	v_rcp_f32_e32 v5, v5
	v_lshlrev_b32_e32 v9, 16, v39
	v_fmac_f32_e32 v9, v6, v3
	v_and_b32_e32 v6, 0xffff0000, v39
	v_fmac_f32_e32 v6, v7, v5
	v_cvt_pk_bf16_f32 v2, v2, v8
	v_cvt_pk_bf16_f32 v3, v0, v10
	v_cvt_pk_bf16_f32 v4, v11, v4
	v_cvt_pk_bf16_f32 v5, v9, v6
	global_store_dwordx4 v[16:17], v[2:5], off offset:256 sc0 sc1
	s_cmp_eq_u32 s100, 2
	s_cbranch_scc0 .Lpp5_nf
	s_waitcnt vmcnt(0)
	s_barrier
	v_readfirstlane_b32 s8, v166
	s_nop 0
	s_cmp_lt_u32 s8, 64
	s_cbranch_scc0 .Lpp5_nf
	v_readlane_b32 s9, v252, 2
	s_lshr_b32 s9, s9, 9
	s_xor_b32 s9, s9, 1
	s_lshl_b32 s9, s9, 2
	s_addk_i32 s9, 0x3700
	v_mov_b32_e32 v120, s9
	v_mov_b32_e32 v121, 1
	s_add_u32 s20, s26, 0x1d780000
	s_addc_u32 s21, s27, 0
	global_store_dword v120, v121, s[20:21] sc0 sc1
